# first grid barrier: issue the 16 per-XCC census loads back-to-back and wait once (was one round trip per load)
# baseline (speedup 1.0000x reference)
; __device__ __forceinline__ unsigned xb_ld(unsigned* p)              { return __hip_atomic_load(p, __ATOMIC_RELAXED, __HIP_MEMORY_SCOPE_AGENT); }
; __device__ __forceinline__ void xcd_barrier_complete(unsigned* bar, unsigned x, unsigned& nloc, unsigned& nx) {
;     ...
;     for (;;) {
;         sum = 0u; cnt = 0u; mine = 0u;
; #pragma unroll
;         for (unsigned j = 0; j < 16; ++j) { const unsigned c = xb_ld(&bar[XB_XCNT(j)]); sum += c; cnt += (c > 0u) ? 1u : 0u; mine = (j == x) ? c : mine; }
;         if (sum == G) break;
;         __builtin_amdgcn_s_sleep(1);
;         if ((++sp & 255u) == 0u) { if (xb_ld(&bar[XB_TMO])) break; if (sp > XB_SPIN_CAP) { atomicAdd(&bar[XB_TMO], 1u); break; } }
;     }
.LBB0_208:
	v_readlane_b32 s4, v246, 28
	v_readlane_b32 s5, v246, 29
	s_mov_b64 s[18:19], -1
	s_mov_b64 s[24:25], -1
	s_waitcnt lgkmcnt(0)
	s_nop 1
	global_load_dword v0, v1, s[4:5] sc1
	v_readlane_b32 s4, v246, 30
	v_readlane_b32 s5, v246, 31
	s_nop 4
	global_load_dword v2, v1, s[4:5] sc1
	v_readlane_b32 s4, v246, 32
	v_readlane_b32 s5, v246, 33
	s_nop 4
	global_load_dword v3, v1, s[4:5] sc1
	v_readlane_b32 s4, v246, 34
	v_readlane_b32 s5, v246, 35
	s_nop 4
	global_load_dword v4, v1, s[4:5] sc1
	v_readlane_b32 s4, v246, 36
	v_readlane_b32 s5, v246, 37
	s_nop 4
	global_load_dword v5, v1, s[4:5] sc1
	v_readlane_b32 s4, v246, 38
	v_readlane_b32 s5, v246, 39
	s_nop 4
	global_load_dword v6, v1, s[4:5] sc1
	v_readlane_b32 s4, v246, 40
	v_readlane_b32 s5, v246, 41
	s_nop 4
	global_load_dword v7, v1, s[4:5] sc1
	v_readlane_b32 s4, v246, 42
	v_readlane_b32 s5, v246, 43
	s_nop 4
	global_load_dword v8, v1, s[4:5] sc1
	v_readlane_b32 s4, v246, 44
	v_readlane_b32 s5, v246, 45
	s_nop 4
	global_load_dword v9, v1, s[4:5] sc1
	v_readlane_b32 s4, v246, 46
	v_readlane_b32 s5, v246, 47
	s_nop 4
	global_load_dword v10, v1, s[4:5] sc1
	v_readlane_b32 s4, v246, 48
	v_readlane_b32 s5, v246, 49
	s_nop 4
	global_load_dword v11, v1, s[4:5] sc1
	v_readlane_b32 s4, v246, 50
	v_readlane_b32 s5, v246, 51
	s_nop 4
	global_load_dword v12, v1, s[4:5] sc1
	v_readlane_b32 s4, v246, 52
	v_readlane_b32 s5, v246, 53
	s_nop 4
	global_load_dword v13, v1, s[4:5] sc1
	v_readlane_b32 s4, v246, 54
	v_readlane_b32 s5, v246, 55
	s_nop 4
	global_load_dword v14, v1, s[4:5] sc1
	v_readlane_b32 s4, v246, 56
	v_readlane_b32 s5, v246, 57
	s_nop 4
	global_load_dword v15, v1, s[4:5] sc1
	v_readlane_b32 s4, v246, 58
	v_readlane_b32 s5, v246, 59
	s_nop 4
	global_load_dword v16, v1, s[4:5] sc1
	s_waitcnt vmcnt(0)
	v_add_u32_e32 v17, v2, v0
	v_add_u32_e32 v17, v17, v3
	v_add_u32_e32 v17, v17, v4
	v_add_u32_e32 v17, v17, v5
	v_add_u32_e32 v17, v17, v6
	v_add_u32_e32 v17, v17, v7
	v_add_u32_e32 v17, v17, v8
	v_add_u32_e32 v17, v17, v9
	v_add_u32_e32 v17, v17, v10
	v_add_u32_e32 v17, v17, v11
	v_add_u32_e32 v17, v17, v12
	v_add_u32_e32 v17, v17, v13
	v_add_u32_e32 v17, v17, v14
	v_add_u32_e32 v17, v17, v15
	v_add_u32_e32 v17, v17, v16
	v_cmp_eq_u32_e32 vcc, s71, v17
	s_cbranch_vccnz .LBB0_207
	s_and_b32 s4, s2, 0xff
	s_cmp_eq_u32 s4, 0
	s_mov_b64 s[26:27], -1
	s_sleep 1
	s_cbranch_scc0 .LBB0_212
	v_readlane_b32 s4, v246, 26
	v_readlane_b32 s5, v246, 27
	s_nop 4
	global_load_dword v17, v1, s[4:5] sc1
	s_waitcnt vmcnt(0)
	v_cmp_eq_u32_e32 vcc, 0, v17
	s_cbranch_vccnz .LBB0_214
	s_mov_b64 s[26:27], 0
